# combo + ATTN next-unit prefetch under epilogue + XCD-local barriers (runtime-verified placement) for RC1->RC23 and P5->P6
# baseline (speedup 1.0000x reference)
.LBB0_298:
	s_cmp_gt_i32 s83, 1
	s_cselect_b64 s[0:1], -1, 0
	s_and_b64 s[4:5], s[4:5], s[0:1]
	v_writelane_b32 v238, s42, 36
	s_andn2_b64 vcc, exec, s[4:5]
	s_nop 0
	v_writelane_b32 v238, s43, 37
	v_writelane_b32 v238, s44, 38
	s_cbranch_vccnz .LBB0_352
	s_waitcnt vmcnt(0)
	s_barrier
	s_and_saveexec_b64 s[4:5], s[42:43]
	s_cbranch_execz .LBB0_351
	s_and_b32 s100, s86, 7
	s_cmp_eq_u32 s100, s87
	s_cbranch_scc1 .Lxl_ok
	v_readlane_b32 s100, v238, 18
	v_readlane_b32 s101, v238, 19
	v_mov_b32_e32 v1, 0x3f00
	v_mov_b32_e32 v3, 1
	s_nop 4
	global_atomic_add v1, v3, s[100:101]
.Lxl_ok:
	s_add_i32 s2, 0, 0x25f20
	s_waitcnt vmcnt(0)
	v_mov_b32_e32 v1, s2
	s_waitcnt vmcnt(0) expcnt(0) lgkmcnt(0)
	ds_read_b32 v3, v1
	s_add_i32 s2, 0, 0x25f24
	v_mov_b32_e32 v1, s2
	ds_read_b32 v1, v1
	s_waitcnt lgkmcnt(1)
	v_cmp_ne_u32_e32 vcc, 0, v3
	s_cbranch_vccnz .LBB0_315
	v_readlane_b32 s6, v238, 0
	v_readlane_b32 s7, v238, 1
	s_load_dwordx2 s[10:11], s[6:7], 0x4
	s_add_u32 s6, s80, 0x4200
	s_addc_u32 s7, s81, 0
	s_add_u32 s8, s80, 0x4400
	s_addc_u32 s9, s81, 0
	s_waitcnt lgkmcnt(0)
	s_mul_i32 s2, s10, s3
	s_add_u32 s10, s80, 0x4500
	s_mul_i32 s2, s2, s11
	s_addc_u32 s11, s81, 0
	s_add_u32 s12, s80, 0x4600
	s_addc_u32 s13, s81, 0
	s_add_u32 s14, s80, 0x4700
	s_addc_u32 s15, s81, 0
	s_add_u32 s16, s80, 0x4800
	s_addc_u32 s17, s81, 0
	s_add_u32 s18, s80, 0x4900
	s_addc_u32 s19, s81, 0
	s_add_u32 s20, s80, 0x4a00
	s_addc_u32 s21, s81, 0
	s_add_u32 s22, s80, 0x4b00
	s_addc_u32 s23, s81, 0
	s_add_u32 s24, s80, 0x4c00
	s_addc_u32 s25, s81, 0
	s_add_u32 s26, s80, 0x4d00
	s_addc_u32 s27, s81, 0
	s_add_u32 s28, s80, 0x4e00
	s_addc_u32 s29, s81, 0
	s_add_u32 s30, s80, 0x4f00
	s_addc_u32 s31, s81, 0
	s_add_u32 s34, s80, 0x5000
	s_addc_u32 s35, s81, 0
	s_add_u32 s36, s80, 0x5100
	s_addc_u32 s37, s81, 0
	s_add_u32 s38, s80, 0x5200
	s_addc_u32 s39, s81, 0
	s_add_u32 s40, s80, 0x5300
	s_addc_u32 s41, s81, 0
	s_mov_b32 s33, 1
	v_mov_b32_e32 v17, 0
	s_branch .LBB0_303

.LBB0_510:
	s_cmp_gt_i32 s83, 2
	s_cselect_b64 s[0:1], -1, 0
	s_and_b64 s[4:5], s[10:11], s[0:1]
	v_readlane_b32 s38, v238, 36
	s_andn2_b64 vcc, exec, s[4:5]
	v_readlane_b32 s39, v238, 37
	s_mov_b32 s40, s92
	s_cbranch_vccnz .LBB0_564
	s_waitcnt vmcnt(0)
	s_waitcnt vmcnt(0)
	s_barrier
	s_and_saveexec_b64 s[4:5], s[38:39]
	s_cbranch_execz .LBB0_563
	s_add_u32 s98, s98, 1
	v_readlane_b32 s6, v238, 18
	v_readlane_b32 s7, v238, 19
	v_mov_b32_e32 v1, 0x3f00
	s_nop 3
	global_load_dword v2, v1, s[6:7] sc1
	s_waitcnt vmcnt(0)
	v_readfirstlane_b32 s2, v2
	s_nop 0
	v_writelane_b32 v238, s2, 63
	v_mov_b32_e32 v1, 0x25f20
	ds_read_b64 v[2:3], v1
	s_lshl_b32 s2, s87, 8
	s_addk_i32 s2, 0x1400
	v_mov_b32_e32 v1, s2
	v_mov_b32_e32 v5, 1
	v_readlane_b32 s12, v238, 63
	s_waitcnt lgkmcnt(0)
	v_readfirstlane_b32 s9, v2
	v_readfirstlane_b32 s10, v3
	s_mul_i32 s9, s9, s98
	s_cmp_lg_u32 s12, 0
	s_cselect_b32 s12, s98, 2
	s_mul_i32 s10, s10, s12
	global_atomic_add v1, v1, v5, s[6:7] sc0
	s_waitcnt vmcnt(0)
	v_readfirstlane_b32 s12, v1
	s_add_u32 s12, s12, 1
	v_mov_b32_e32 v1, 0x3400
	s_cmp_eq_u32 s12, s9
	s_cbranch_scc0 .Lfs0_spin
	buffer_wbl2 sc1
	s_waitcnt vmcnt(0)
	global_atomic_add v1, v5, s[6:7]

.LBB0_855:
	s_cmp_gt_i32 s83, 4
	s_cselect_b64 s[0:1], -1, 0
	s_and_b64 s[4:5], s[6:7], s[0:1]
	s_andn2_b64 vcc, exec, s[4:5]
	s_cbranch_vccnz .LBB0_909
	s_waitcnt vmcnt(0)
	s_waitcnt vmcnt(0) lgkmcnt(0)
	s_barrier
	s_and_saveexec_b64 s[4:5], s[38:39]
	s_cbranch_execz .LBB0_908
	s_add_u32 s98, s98, 1
	v_readlane_b32 s6, v238, 18
	v_readlane_b32 s7, v238, 19
	v_mov_b32_e32 v1, 0x25f20
	ds_read_b64 v[2:3], v1
	s_lshl_b32 s2, s87, 8
	s_addk_i32 s2, 0x1400
	v_mov_b32_e32 v1, s2
	v_mov_b32_e32 v5, 1
	v_readlane_b32 s12, v238, 63
	s_waitcnt lgkmcnt(0)
	v_readfirstlane_b32 s9, v2
	v_readfirstlane_b32 s10, v3
	s_mul_i32 s9, s9, s98
	s_cmp_lg_u32 s12, 0
	s_cselect_b32 s12, s98, 3
	s_mul_i32 s10, s10, s12
	global_atomic_add v1, v1, v5, s[6:7] sc0
	s_waitcnt vmcnt(0)
	v_readfirstlane_b32 s12, v1
	s_add_u32 s12, s12, 1
	v_mov_b32_e32 v1, 0x3400
	s_cmp_eq_u32 s12, s9
	s_cbranch_scc0 .Lfs1_spin
	buffer_wbl2 sc1
	s_waitcnt vmcnt(0)
	global_atomic_add v1, v5, s[6:7]

.LBB0_946:
	v_add_f32_e32 v16, v16, v17
	v_add_f32_e32 v180, v180, v181
	v_lshlrev_b32_e32 v3, 2, v176
	s_lshl_b32 s6, s93, 8
	s_add_i32 s6, s6, 0xc000
	v_add_f32_e32 v16, v16, v180
	v_add_u32_e32 v3, s6, v3
	v_lshrrev_b32_e32 v4, 5, v176
	v_lshl_add_u32 v4, v4, 4, s6
	ds_write_b32 v3, v16
	s_waitcnt lgkmcnt(0)
	ds_read2_b32 v[66:67], v4 offset0:0 offset1:32
	ds_read2_b32 v[68:69], v4 offset0:1 offset1:33
	ds_read2_b32 v[70:71], v4 offset0:2 offset1:34
	ds_read2_b32 v[72:73], v4 offset0:3 offset1:35
	ds_read2_b32 v[74:75], v4 offset0:8 offset1:40
	ds_read2_b32 v[76:77], v4 offset0:9 offset1:41
	ds_read2_b32 v[78:79], v4 offset0:10 offset1:42
	ds_read2_b32 v[80:81], v4 offset0:11 offset1:43
	ds_read2_b32 v[82:83], v4 offset0:16 offset1:48
	ds_read2_b32 v[84:85], v4 offset0:17 offset1:49
	ds_read2_b32 v[86:87], v4 offset0:18 offset1:50
	ds_read2_b32 v[88:89], v4 offset0:19 offset1:51
	ds_read2_b32 v[90:91], v4 offset0:24 offset1:56
	ds_read2_b32 v[92:93], v4 offset0:25 offset1:57
	ds_read2_b32 v[94:95], v4 offset0:26 offset1:58
	ds_read2_b32 v[96:97], v4 offset0:27 offset1:59
	s_waitcnt lgkmcnt(0)
	v_add_f32_e32 v50, v66, v67
	v_add_f32_e32 v51, v68, v69
	v_add_f32_e32 v52, v70, v71
	v_add_f32_e32 v53, v72, v73
	v_add_f32_e32 v54, v74, v75
	v_add_f32_e32 v55, v76, v77
	v_add_f32_e32 v56, v78, v79
	v_add_f32_e32 v57, v80, v81
	v_add_f32_e32 v58, v82, v83
	v_add_f32_e32 v59, v84, v85
	v_add_f32_e32 v60, v86, v87
	v_add_f32_e32 v61, v88, v89
	v_add_f32_e32 v62, v90, v91
	v_add_f32_e32 v63, v92, v93
	v_add_f32_e32 v64, v94, v95
	v_add_f32_e32 v65, v96, v97
	s_nop 2
	v_rcp_f32_e32 v3, v50
	v_rcp_f32_e32 v4, v51
	s_waitcnt vmcnt(0)
	s_cmp_eq_u32 s26, 3
	s_cbranch_scc1 .Lat_nopf
	s_cmp_eq_u32 s26, 0
	s_cselect_b32 s36, s17, s18
	s_cmp_eq_u32 s26, 2
	s_cselect_b32 s36, s19, s36
	s_lshl_b32 s36, s36, 8
	s_add_i32 s36, s36, s16
	s_add_u32 s6, s8, s36
	s_addc_u32 s7, s9, 0
	s_lshl_b64 s[6:7], s[6:7], 10
	v_lshl_add_u64 v[150:151], v[114:115], 0, s[6:7]
	s_mov_b32 s6, s36
	s_mov_b32 s7, 0
	v_lshl_add_u64 v[136:137], s[6:7], 3, v[120:121]
	s_waitcnt lgkmcnt(0)
	s_barrier
	global_load_dwordx4 v[98:101], v[150:151], off offset:32
	global_load_dwordx4 v[102:105], v[150:151], off offset:64
	global_load_dwordx4 v[106:109], v[150:151], off offset:96
	global_load_dwordx4 v[110:113], v[150:151], off
	global_load_dwordx2 v[138:139], v[136:137], off
	s_mov_b64 s[6:7], 0x8000
	v_lshl_add_u64 v[150:151], v[136:137], 0, s[6:7]
	global_load_dwordx2 v[180:181], v[150:151], off
	s_mov_b32 m0, s21
	s_nop 0
	global_load_lds_dwordx4 v[116:117], off
	s_mov_b32 m0, s22
	s_nop 0
	global_load_lds_dwordx4 v[118:119], off
	s_mov_b32 m0, s23
	s_nop 0
	global_load_lds_dwordx4 v[122:123], off
	s_mov_b32 m0, s24
	s_nop 0
	global_load_lds_dwordx4 v[124:125], off
.Lat_nopf:
	v_rcp_f32_e32 v5, v52
	v_mul_f32_e32 v34, v3, v34
	v_mul_f32_e32 v3, v18, v3
	v_cvt_pk_bf16_f32 v3, v3, s0
	ds_write_b16 v143, v3 offset:51264
	v_mul_f32_e32 v3, v4, v35
	v_cvt_pk_bf16_f32 v3, v3, s0
	ds_write_b16 v143, v3 offset:51328
	v_mul_f32_e32 v3, v19, v4
	v_cvt_pk_bf16_f32 v3, v3, s0
	v_rcp_f32_e32 v6, v53
	ds_write_b16 v143, v3 offset:51392
	v_mul_f32_e32 v3, v5, v36
	v_cvt_pk_bf16_f32 v3, v3, s0
	ds_write_b16 v143, v3 offset:51456
	v_mul_f32_e32 v3, v20, v5
	v_cvt_pk_bf16_f32 v3, v3, s0
	v_rcp_f32_e32 v7, v54
	ds_write_b16 v143, v3 offset:51520
	v_mul_f32_e32 v3, v6, v37
	v_cvt_pk_bf16_f32 v3, v3, s0
	ds_write_b16 v143, v3 offset:51584
	v_mul_f32_e32 v3, v21, v6
	v_cvt_pk_bf16_f32 v3, v3, s0
	v_rcp_f32_e32 v8, v55
	ds_write_b16 v143, v3 offset:51648
	v_mul_f32_e32 v3, v7, v38
	v_cvt_pk_bf16_f32 v3, v3, s0
	ds_write_b16 v143, v3 offset:52224
	v_mul_f32_e32 v3, v22, v7
	v_cvt_pk_bf16_f32 v3, v3, s0
	v_rcp_f32_e32 v9, v56
	ds_write_b16 v143, v3 offset:52288
	v_mul_f32_e32 v3, v8, v39
	v_cvt_pk_bf16_f32 v3, v3, s0
	ds_write_b16 v143, v3 offset:52352
	v_mul_f32_e32 v3, v23, v8
	v_cvt_pk_bf16_f32 v3, v3, s0
	v_rcp_f32_e32 v10, v57
	ds_write_b16 v143, v3 offset:52416
	v_mul_f32_e32 v3, v9, v40
	v_cvt_pk_bf16_f32 v3, v3, s0
	ds_write_b16 v143, v3 offset:52480
	v_mul_f32_e32 v3, v24, v9
	v_cvt_pk_bf16_f32 v3, v3, s0
	v_rcp_f32_e32 v11, v58
	ds_write_b16 v143, v3 offset:52544
	v_mul_f32_e32 v3, v10, v41
	v_cvt_pk_bf16_f32 v3, v3, s0
	ds_write_b16 v143, v3 offset:52608
	v_mul_f32_e32 v3, v25, v10
	v_cvt_pk_bf16_f32 v3, v3, s0
	v_rcp_f32_e32 v12, v59
	ds_write_b16 v143, v3 offset:52672
	v_mul_f32_e32 v3, v11, v42
	v_cvt_pk_bf16_f32 v3, v3, s0
	ds_write_b16 v143, v3 offset:53248
	v_mul_f32_e32 v3, v26, v11
	v_cvt_pk_bf16_f32 v3, v3, s0
	v_rcp_f32_e32 v13, v60
	ds_write_b16 v143, v3 offset:53312
	v_mul_f32_e32 v3, v12, v43
	v_cvt_pk_bf16_f32 v3, v3, s0
	ds_write_b16 v143, v3 offset:53376
	v_mul_f32_e32 v3, v27, v12
	v_cvt_pk_bf16_f32 v3, v3, s0
	v_rcp_f32_e32 v14, v61
	ds_write_b16 v143, v3 offset:53440
	v_mul_f32_e32 v3, v13, v44
	v_cvt_pk_bf16_f32 v3, v3, s0
	ds_write_b16 v143, v3 offset:53504
	v_mul_f32_e32 v3, v28, v13
	v_cvt_pk_bf16_f32 v3, v3, s0
	v_rcp_f32_e32 v15, v62
	ds_write_b16 v143, v3 offset:53568
	v_mul_f32_e32 v3, v14, v45
	v_cvt_pk_bf16_f32 v3, v3, s0
	ds_write_b16 v143, v3 offset:53632
	v_mul_f32_e32 v3, v29, v14
	v_cvt_pk_bf16_f32 v3, v3, s0
	v_rcp_f32_e32 v16, v63
	ds_write_b16 v143, v3 offset:53696
	v_mul_f32_e32 v3, v15, v46
	v_cvt_pk_bf16_f32 v3, v3, s0
	ds_write_b16 v143, v3 offset:54272
	v_mul_f32_e32 v3, v30, v15
	v_cvt_pk_bf16_f32 v3, v3, s0
	v_rcp_f32_e32 v17, v64
	ds_write_b16 v143, v3 offset:54336
	v_mul_f32_e32 v3, v16, v47
	v_cvt_pk_bf16_f32 v3, v3, s0
	ds_write_b16 v143, v3 offset:54400
	v_mul_f32_e32 v3, v31, v16
	v_cvt_pk_bf16_f32 v3, v3, s0
	v_rcp_f32_e32 v50, v65
	ds_write_b16 v143, v3 offset:54464
	v_mul_f32_e32 v3, v17, v48
	v_cvt_pk_bf16_f32 v3, v3, s0
	ds_write_b16 v143, v3 offset:54528
	v_mul_f32_e32 v3, v32, v17
	v_cvt_pk_bf16_f32 v3, v3, s0
	ds_write_b16 v143, v3 offset:54592
	v_mul_f32_e32 v3, v50, v49
	v_cvt_pk_bf16_f32 v3, v3, s0
	ds_write_b16 v143, v3 offset:54656
	v_mul_f32_e32 v3, v33, v50
	v_cvt_pk_bf16_f32 v34, v34, s0
	v_cvt_pk_bf16_f32 v3, v3, s0
	ds_write_b16 v143, v34 offset:51200
	ds_write_b16 v143, v3 offset:54720
	s_waitcnt lgkmcnt(0)
	ds_read_b128 v[4:7], v144 offset:51200
	ds_read_b128 v[8:11], v145 offset:51200
	s_lshl_b64 s[6:7], s[12:13], 11
	v_lshl_add_u64 v[16:17], v[126:127], 0, s[6:7]
	v_lshl_add_u64 v[12:13], v[16:17], 0, v[128:129]
	s_waitcnt lgkmcnt(1)
	global_store_dwordx4 v[12:13], v[4:7], off
	ds_read_b128 v[4:7], v146 offset:51200
	ds_read_b128 v[12:15], v147 offset:51200
	v_lshl_add_u64 v[18:19], v[16:17], 0, v[130:131]
	s_waitcnt lgkmcnt(2)
	global_store_dwordx4 v[18:19], v[8:11], off
	s_add_i32 s26, s26, 1
	s_cmp_eq_u32 s26, 4
	v_lshl_add_u64 v[8:9], v[16:17], 0, v[132:133]
	s_waitcnt lgkmcnt(1)
	global_store_dwordx4 v[8:9], v[4:7], off
	s_nop 1
	v_lshl_add_u64 v[4:5], v[16:17], 0, v[134:135]
	s_waitcnt lgkmcnt(0)
	global_store_dwordx4 v[4:5], v[12:15], off
	s_waitcnt lgkmcnt(0)
	s_cbranch_scc1 .LBB0_958

.LBB0_952:
	s_lshl_b32 s6, s5, 8
	s_add_i32 s14, s6, s16
	s_add_u32 s12, s8, s14
	s_addc_u32 s13, s9, 0
	s_lshl_b64 s[6:7], s[12:13], 10
	v_lshl_add_u64 v[4:5], v[114:115], 0, s[6:7]
	s_mov_b32 s15, s11
	v_mov_b32_e32 v16, v2
	s_cmp_lg_u32 s26, 0
	s_cbranch_scc1 .Lat_skip
	global_load_dwordx4 v[98:101], v[4:5], off offset:32
	global_load_dwordx4 v[102:105], v[4:5], off offset:64
	global_load_dwordx4 v[106:109], v[4:5], off offset:96
	v_lshl_add_u64 v[136:137], s[14:15], 3, v[120:121]
	global_load_dwordx4 v[110:113], v[4:5], off
	global_load_dwordx2 v[138:139], v[136:137], off
	s_mov_b64 s[36:37], 0x8000
	v_lshl_add_u64 v[150:151], v[136:137], 0, s[36:37]
	global_load_dwordx2 v[180:181], v[150:151], off
	s_waitcnt lgkmcnt(0)
	s_barrier
	s_mov_b32 m0, s21
	global_load_lds_dwordx4 v[116:117], off
	s_mov_b32 m0, s22
	global_load_lds_dwordx4 v[118:119], off
	v_mov_b32_e32 v16, v2
	s_mov_b32 m0, s23
	global_load_lds_dwordx4 v[122:123], off
	s_mov_b32 m0, s24
	global_load_lds_dwordx4 v[124:125], off
.Lat_skip:
	s_waitcnt vmcnt(2)
	v_mov_b32_e32 v17, v2
	s_lshl_b32 s6, s5, 2
	s_lshl_b32 s30, s5, 10
	v_mov_b32_e32 v3, v2
	v_mov_b32_e32 v4, v2
	v_mov_b32_e32 v5, v2
	v_mov_b32_e32 v6, v2
	v_mov_b32_e32 v7, v2
	v_mov_b32_e32 v8, v2
	v_mov_b32_e32 v9, v2
	v_mov_b32_e32 v10, v2
	v_mov_b32_e32 v11, v2
	v_mov_b32_e32 v12, v2
	v_mov_b32_e32 v13, v2
	v_mov_b32_e32 v14, v2
	v_mov_b32_e32 v15, v2
	v_mov_b64_e32 v[48:49], v[16:17]
	v_mov_b64_e32 v[32:33], v[16:17]
	v_mov_b64_e32 v[64:65], v[16:17]
	s_mov_b32 s15, 2
	s_add_i32 s27, s6, 4
	s_lshr_b32 s28, s14, 6
	s_or_b32 s29, s6, 3
	v_add_u32_e32 v148, s30, v142
	s_addk_i32 s30, 0x400
	s_mov_b32 s31, 0
	s_movk_i32 s33, 0xaf
	v_mov_b64_e32 v[46:47], v[14:15]
	v_mov_b64_e32 v[44:45], v[12:13]
	v_mov_b64_e32 v[42:43], v[10:11]
	v_mov_b64_e32 v[40:41], v[8:9]
	v_mov_b64_e32 v[38:39], v[6:7]
	v_mov_b64_e32 v[36:37], v[4:5]
	v_mov_b64_e32 v[34:35], v[2:3]
	v_mov_b64_e32 v[30:31], v[14:15]
	v_mov_b64_e32 v[28:29], v[12:13]
	v_mov_b64_e32 v[26:27], v[10:11]
	v_mov_b64_e32 v[24:25], v[8:9]
	v_mov_b64_e32 v[22:23], v[6:7]
	v_mov_b64_e32 v[20:21], v[4:5]
	v_mov_b64_e32 v[18:19], v[2:3]
	v_mov_b64_e32 v[62:63], v[14:15]
	v_mov_b64_e32 v[60:61], v[12:13]
	v_mov_b64_e32 v[58:59], v[10:11]
	v_mov_b64_e32 v[56:57], v[8:9]
	v_mov_b64_e32 v[54:55], v[6:7]
	v_mov_b64_e32 v[52:53], v[4:5]
	v_mov_b64_e32 v[50:51], v[2:3]
	s_mov_b32 s34, 0
	v_lshrrev_b32_e32 v3, v1, v138
	v_lshlrev_b32_e32 v3, 4, v3
	v_and_b32_e32 v177, 0xf0f0f0f0, v3
	v_lshrrev_b32_e32 v3, v1, v139
	v_lshlrev_b32_e32 v3, 4, v3
	v_and_b32_e32 v179, 0xf0f0f0f0, v3
	v_mov_b64_e32 v[138:139], v[180:181]
	v_mov_b32_e32 v180, 0
	v_mov_b32_e32 v181, 0
	v_mov_b32_e32 v16, 0
	v_mov_b32_e32 v17, 0
	s_branch .LBB0_955

.LBB0_959:
	s_cmp_gt_i32 s83, 7
	s_cselect_b64 s[4:5], -1, 0
	s_and_b64 s[0:1], s[0:1], s[4:5]
	s_andn2_b64 vcc, exec, s[0:1]
	s_cbranch_vccnz .LBB0_1013
	s_waitcnt vmcnt(0)
	s_waitcnt vmcnt(0) lgkmcnt(0)
	s_barrier
	s_and_saveexec_b64 s[0:1], s[38:39]
	s_cbranch_execz .LBB0_1012
	s_add_u32 s98, s98, 1
	v_readlane_b32 s6, v238, 18
	v_readlane_b32 s7, v238, 19
	v_mov_b32_e32 v1, 0x25f20
	ds_read_b64 v[2:3], v1
	s_lshl_b32 s2, s87, 8
	s_addk_i32 s2, 0x1400
	v_mov_b32_e32 v1, s2
	v_mov_b32_e32 v5, 1
	v_readlane_b32 s12, v238, 63
	s_waitcnt lgkmcnt(0)
	v_readfirstlane_b32 s9, v2
	v_readfirstlane_b32 s10, v3
	s_mul_i32 s9, s9, s98
	s_cmp_lg_u32 s12, 0
	s_cselect_b32 s12, s98, 4
	s_mul_i32 s10, s10, s12
	global_atomic_add v1, v1, v5, s[6:7] sc0
	s_waitcnt vmcnt(0)
	v_readfirstlane_b32 s12, v1
	s_add_u32 s12, s12, 1
	v_mov_b32_e32 v1, 0x3400
	s_cmp_eq_u32 s12, s9
	s_cbranch_scc0 .Lfs2_spin
	buffer_wbl2 sc1
	s_waitcnt vmcnt(0)
	global_atomic_add v1, v5, s[6:7]

.LBB0_1147:
	s_barrier
	s_waitcnt vmcnt(0)
	v_readlane_b32 s38, v238, 36
	v_readlane_b32 s39, v238, 37
	s_barrier
	s_and_saveexec_b64 s[0:1], s[38:39]
	v_readlane_b32 s86, v238, 47
	v_readlane_b32 s87, v238, 46
	v_readlane_b32 s40, v238, 58
	v_readlane_b32 s93, v238, 48
	v_readlane_b32 s24, v238, 38
	v_readlane_b32 s41, v238, 59
	s_cbranch_execz .LBB0_1199
	s_add_u32 s98, s98, 1
	v_readlane_b32 s6, v238, 18
	v_readlane_b32 s7, v238, 19
	v_mov_b32_e32 v1, 0x25f20
	ds_read_b64 v[2:3], v1
	s_lshl_b32 s2, s87, 8
	s_addk_i32 s2, 0x1400
	v_mov_b32_e32 v1, s2
	v_mov_b32_e32 v5, 1
	v_readlane_b32 s12, v238, 63
	s_waitcnt lgkmcnt(0)
	v_readfirstlane_b32 s9, v2
	v_readfirstlane_b32 s10, v3
	s_mul_i32 s9, s9, s98
	s_cmp_lg_u32 s12, 0
	s_cbranch_scc1 .Lfs3_glob
	global_atomic_add v1, v5, s[6:7]
	s_mov_b32 s11, 0
.Lfs3_lloop:
	global_load_dword v2, v1, s[6:7] sc1
	s_add_u32 s11, s11, 1
	s_waitcnt vmcnt(0)
	v_readfirstlane_b32 s12, v2
	s_cmp_ge_u32 s12, s9
	s_cbranch_scc1 .Lfs3_done
	s_sleep 1
	s_cmp_lt_u32 s11, 0x100000
	s_cbranch_scc1 .Lfs3_lloop
	s_branch .Lfs3_done
.Lfs3_glob:
	s_mul_i32 s10, s10, s98
	global_atomic_add v1, v1, v5, s[6:7] sc0
	s_waitcnt vmcnt(0)
	v_readfirstlane_b32 s12, v1
	s_add_u32 s12, s12, 1
	v_mov_b32_e32 v1, 0x3400
	s_cmp_eq_u32 s12, s9
	s_cbranch_scc0 .Lfs3_spin
	buffer_wbl2 sc1
	s_waitcnt vmcnt(0)
	global_atomic_add v1, v5, s[6:7]

.LBB0_1221:
	s_cmp_gt_i32 s83, 8
	s_cselect_b64 s[0:1], -1, 0
	s_and_b64 s[4:5], s[4:5], s[0:1]
	s_andn2_b64 vcc, exec, s[4:5]
	s_mov_b64 s[60:61], s[38:39]
	s_cbranch_vccnz .LBB0_1275
	s_waitcnt vmcnt(0)
	s_waitcnt vmcnt(0) lgkmcnt(0)
	s_barrier
	s_and_saveexec_b64 s[4:5], s[38:39]
	s_cbranch_execz .LBB0_1274
	s_add_u32 s98, s98, 1
	v_readlane_b32 s6, v238, 18
	v_readlane_b32 s7, v238, 19
	v_mov_b32_e32 v1, 0x25f20
	ds_read_b64 v[2:3], v1
	s_lshl_b32 s2, s87, 8
	s_addk_i32 s2, 0x1400
	v_mov_b32_e32 v1, s2
	v_mov_b32_e32 v5, 1
	v_readlane_b32 s12, v238, 63
	s_waitcnt lgkmcnt(0)
	v_readfirstlane_b32 s9, v2
	v_readfirstlane_b32 s10, v3
	s_mul_i32 s9, s9, s98
	s_cmp_lg_u32 s12, 0
	s_cselect_b32 s12, s98, 5
	s_mul_i32 s10, s10, s12
	global_atomic_add v1, v1, v5, s[6:7] sc0
	s_waitcnt vmcnt(0)
	v_readfirstlane_b32 s12, v1
	s_add_u32 s12, s12, 1
	v_mov_b32_e32 v1, 0x3400
	s_cmp_eq_u32 s12, s9
	s_cbranch_scc0 .Lfs4_spin
	buffer_wbl2 sc1
	s_waitcnt vmcnt(0)
	global_atomic_add v1, v5, s[6:7]

.LBB0_1279:
	s_cmp_gt_i32 s83, 9
	s_cselect_b64 s[0:1], -1, 0
	s_and_b64 s[4:5], s[6:7], s[0:1]
	s_andn2_b64 vcc, exec, s[4:5]
	s_cbranch_vccnz .LBB0_1333
	s_waitcnt vmcnt(0)
	s_waitcnt vmcnt(0) lgkmcnt(0)
	s_barrier
	s_and_saveexec_b64 s[4:5], s[38:39]
	s_cbranch_execz .LBB0_1332
	s_add_u32 s98, s98, 1
	v_readlane_b32 s6, v238, 18
	v_readlane_b32 s7, v238, 19
	v_mov_b32_e32 v1, 0x25f20
	ds_read_b64 v[2:3], v1
	s_lshl_b32 s2, s87, 8
	s_addk_i32 s2, 0x1400
	v_mov_b32_e32 v1, s2
	v_mov_b32_e32 v5, 1
	v_readlane_b32 s12, v238, 63
	s_waitcnt lgkmcnt(0)
	v_readfirstlane_b32 s9, v2
	v_readfirstlane_b32 s10, v3
	s_mul_i32 s9, s9, s98
	s_cmp_lg_u32 s12, 0
	s_cselect_b32 s12, s98, 6
	s_mul_i32 s10, s10, s12
	global_atomic_add v1, v1, v5, s[6:7] sc0
	s_waitcnt vmcnt(0)
	v_readfirstlane_b32 s12, v1
	s_add_u32 s12, s12, 1
	v_mov_b32_e32 v1, 0x3400
	s_cmp_eq_u32 s12, s9
	s_cbranch_scc0 .Lfs5_spin
	buffer_wbl2 sc1
	s_waitcnt vmcnt(0)
	global_atomic_add v1, v5, s[6:7]

.LBB0_1360:
	s_cmp_lt_i32 s82, 11
	s_cselect_b64 s[4:5], -1, 0
	s_cmp_gt_i32 s83, 11
	s_cselect_b64 s[0:1], -1, 0
	s_and_b64 s[4:5], s[4:5], s[0:1]
	s_andn2_b64 vcc, exec, s[4:5]
	s_cbranch_vccnz .LBB0_1414
	s_waitcnt vmcnt(0)
	s_waitcnt vmcnt(0) lgkmcnt(0)
	s_barrier
	s_and_saveexec_b64 s[4:5], s[38:39]
	s_cbranch_execz .LBB0_1413
	s_add_u32 s98, s98, 1
	v_readlane_b32 s6, v238, 18
	v_readlane_b32 s7, v238, 19
	v_mov_b32_e32 v1, 0x25f20
	ds_read_b64 v[2:3], v1
	s_lshl_b32 s2, s87, 8
	s_addk_i32 s2, 0x1400
	v_mov_b32_e32 v1, s2
	v_mov_b32_e32 v5, 1
	v_readlane_b32 s12, v238, 63
	s_waitcnt lgkmcnt(0)
	v_readfirstlane_b32 s9, v2
	v_readfirstlane_b32 s10, v3
	s_mul_i32 s9, s9, s98
	s_cmp_lg_u32 s12, 0
	s_cselect_b32 s12, s98, 7
	s_mul_i32 s10, s10, s12
	global_atomic_add v1, v1, v5, s[6:7] sc0
	s_waitcnt vmcnt(0)
	v_readfirstlane_b32 s12, v1
	s_add_u32 s12, s12, 1
	v_mov_b32_e32 v1, 0x3400
	s_cmp_eq_u32 s12, s9
	s_cbranch_scc0 .Lfs6_spin
	buffer_wbl2 sc1
	s_waitcnt vmcnt(0)
	global_atomic_add v1, v5, s[6:7]

.LBB0_1437:
	v_lshl_add_u32 v164, s28, 8, v1
	v_lshl_or_b32 v162, s8, 8, v171
	v_readlane_b32 s64, v238, 2
	v_ashrrev_i32_e32 v163, 31, v162
	v_readlane_b32 s65, v238, 3
	v_ashrrev_i32_e32 v165, 31, v164
	v_lshlrev_b64 v[130:131], 12, v[164:165]
	v_lshl_add_u64 v[166:167], v[162:163], 2, s[64:65]
	v_lshl_add_u64 v[130:131], v[166:167], 0, v[130:131]
	global_load_dwordx4 v[176:179], v[130:131], off
	global_load_dwordx4 v[180:183], v[130:131], off offset:16
	global_load_dwordx4 v[184:187], v[130:131], off offset:512
	global_load_dwordx4 v[188:191], v[130:131], off offset:528
	v_or_b32_e32 v168, 16, v164
	v_ashrrev_i32_e32 v169, 31, v168
	v_lshlrev_b64 v[130:131], 12, v[168:169]
	v_lshl_add_u64 v[134:135], v[166:167], 0, v[130:131]
	global_load_dwordx4 v[138:141], v[134:135], off offset:16
	global_load_dwordx4 v[142:145], v[134:135], off
	global_load_dwordx4 v[130:133], v[134:135], off offset:528
	s_nop 0
	global_load_dwordx4 v[134:137], v[134:135], off offset:512
	v_or_b32_e32 v202, 32, v164
	v_ashrrev_i32_e32 v203, 31, v202
	v_lshlrev_b64 v[236:237], 12, v[202:203]
	v_lshl_add_u64 v[236:237], v[166:167], 0, v[236:237]
	global_load_dwordx4 v[204:207], v[236:237], off
	global_load_dwordx4 v[208:211], v[236:237], off offset:16
	global_load_dwordx4 v[212:215], v[236:237], off offset:512
	global_load_dwordx4 v[216:219], v[236:237], off offset:528
	v_or_b32_e32 v202, 48, v164
	v_ashrrev_i32_e32 v203, 31, v202
	v_lshlrev_b64 v[236:237], 12, v[202:203]
	v_lshl_add_u64 v[236:237], v[166:167], 0, v[236:237]
	global_load_dwordx4 v[220:223], v[236:237], off offset:16
	global_load_dwordx4 v[224:227], v[236:237], off
	global_load_dwordx4 v[228:231], v[236:237], off offset:528
	global_load_dwordx4 v[232:235], v[236:237], off offset:512
	v_lshlrev_b64 v[192:193], 11, v[164:165]
	v_lshl_add_u64 v[192:193], s[12:13], 0, v[192:193]
	v_lshl_add_u64 v[192:193], v[162:163], 1, v[192:193]
	s_lshl_b32 s28, s8, 2
	s_ashr_i32 s29, s28, 31
	v_readlane_b32 s66, v238, 4
	v_readlane_b32 s67, v238, 5
	v_readlane_b32 s68, v238, 6
	v_readlane_b32 s69, v238, 7
	v_readlane_b32 s70, v238, 8
	v_readlane_b32 s71, v238, 9
	v_readlane_b32 s72, v238, 10
	v_readlane_b32 s73, v238, 11
	v_readlane_b32 s74, v238, 12
	v_readlane_b32 s75, v238, 13
	v_readlane_b32 s76, v238, 14
	v_readlane_b32 s77, v238, 15
	v_readlane_b32 s78, v238, 16
	v_readlane_b32 s79, v238, 17
	s_waitcnt vmcnt(8)
	v_pk_add_f32 v[126:127], v[126:127], v[176:177]
	v_pk_add_f32 v[128:129], v[128:129], v[178:179]
	v_pk_add_f32 v[124:125], v[124:125], v[182:183]
	v_pk_add_f32 v[122:123], v[122:123], v[180:181]
	v_pk_add_f32 v[178:179], v[118:119], v[184:185]
	v_mul_f32_e32 v184, v127, v127
	v_pk_add_f32 v[176:177], v[120:121], v[186:187]
	v_pk_add_f32 v[180:181], v[116:117], v[190:191]
	v_pk_add_f32 v[182:183], v[114:115], v[188:189]
	v_cvt_pk_bf16_f32 v114, v126, v127
	v_cvt_pk_bf16_f32 v115, v128, v129
	v_cvt_pk_bf16_f32 v116, v122, v123
	v_cvt_pk_bf16_f32 v117, v124, v125
	v_pk_fma_f32 v[126:127], v[126:127], v[126:127], v[184:185] op_sel_hi:[1,1,0]
	v_mul_f32_e32 v186, v129, v129
	v_cvt_pk_bf16_f32 v118, v178, v179
	v_cvt_pk_bf16_f32 v119, v176, v177
	v_cvt_pk_bf16_f32 v120, v182, v183
	v_cvt_pk_bf16_f32 v121, v180, v181
	global_store_dwordx4 v[192:193], v[114:117], off
	global_store_dwordx4 v[192:193], v[118:121], off offset:256
	v_mul_f32_e32 v188, v123, v123
	v_pk_fma_f32 v[114:115], v[128:129], v[128:129], v[126:127]
	v_mul_f32_e32 v190, v125, v125
	v_pk_add_f32 v[114:115], v[186:187], v[114:115] op_sel_hi:[0,1]
	v_pk_fma_f32 v[114:115], v[122:123], v[122:123], v[114:115]
	v_mul_f32_e32 v194, v179, v179
	v_pk_add_f32 v[114:115], v[188:189], v[114:115] op_sel_hi:[0,1]
	v_pk_fma_f32 v[114:115], v[124:125], v[124:125], v[114:115]
	v_mul_f32_e32 v196, v177, v177
	v_pk_add_f32 v[114:115], v[190:191], v[114:115] op_sel_hi:[0,1]
	v_pk_fma_f32 v[114:115], v[178:179], v[178:179], v[114:115]
	v_mul_f32_e32 v198, v183, v183
	v_pk_add_f32 v[114:115], v[194:195], v[114:115] op_sel_hi:[0,1]
	v_pk_fma_f32 v[114:115], v[176:177], v[176:177], v[114:115]
	v_mul_f32_e32 v200, v181, v181
	v_pk_add_f32 v[114:115], v[196:197], v[114:115] op_sel_hi:[0,1]
	v_pk_fma_f32 v[114:115], v[182:183], v[182:183], v[114:115]
	s_nop 0
	v_pk_add_f32 v[114:115], v[198:199], v[114:115] op_sel_hi:[0,1]
	v_pk_fma_f32 v[114:115], v[180:181], v[180:181], v[114:115]
	s_nop 0
	v_pk_add_f32 v[114:115], v[200:201], v[114:115] op_sel_hi:[0,1]
	v_mov_b32_e32 v115, v114
	s_nop 1
	v_permlane16_swap_b32_e32 v114, v115
	v_add_f32_e32 v114, v114, v115
	v_mov_b32_e32 v115, v114
	s_nop 1
	v_permlane32_swap_b32_e32 v114, v115
	s_and_saveexec_b64 s[30:31], s[0:1]
	s_cbranch_execz .LBB0_1439
	v_lshlrev_b64 v[116:117], 6, v[164:165]
	v_lshl_add_u64 v[116:117], s[14:15], 0, v[116:117]
	v_lshl_add_u64 v[116:117], s[28:29], 2, v[116:117]
	s_lshl_b32 s8, s45, 2
	v_lshl_add_u64 v[116:117], v[116:117], 0, s[8:9]
	v_add_f32_e32 v114, v114, v115
	global_store_dword v[116:117], v114, off

.LBB0_1441:
	s_or_b64 exec, exec, s[30:31]
	v_or_b32_e32 v116, 32, v164
	v_ashrrev_i32_e32 v117, 31, v116
	v_lshlrev_b64 v[98:99], 12, v[116:117]
	v_lshl_add_u64 v[98:99], v[166:167], 0, v[98:99]
	v_or_b32_e32 v114, 48, v164
	v_ashrrev_i32_e32 v115, 31, v114
	v_lshlrev_b64 v[98:99], 12, v[114:115]
	v_lshl_add_u64 v[102:103], v[166:167], 0, v[98:99]
	s_nop 0
	s_waitcnt vmcnt(6)
	v_mov_b64_e32 v[118:119], v[204:205]
	v_mov_b64_e32 v[120:121], v[206:207]
	v_mov_b64_e32 v[122:123], v[208:209]
	v_mov_b64_e32 v[124:125], v[210:211]
	v_mov_b64_e32 v[126:127], v[212:213]
	v_mov_b64_e32 v[128:129], v[214:215]
	v_mov_b64_e32 v[130:131], v[216:217]
	v_mov_b64_e32 v[132:133], v[218:219]
	v_mov_b64_e32 v[106:107], v[220:221]
	v_mov_b64_e32 v[108:109], v[222:223]
	v_mov_b64_e32 v[110:111], v[224:225]
	v_mov_b64_e32 v[112:113], v[226:227]
	v_mov_b64_e32 v[98:99], v[228:229]
	v_mov_b64_e32 v[100:101], v[230:231]
	v_mov_b64_e32 v[102:103], v[232:233]
	v_mov_b64_e32 v[104:105], v[234:235]
	v_add_u32_e32 v202, 0x80, v164
	v_ashrrev_i32_e32 v203, 31, v202
	v_lshlrev_b64 v[236:237], 12, v[202:203]
	v_lshl_add_u64 v[236:237], v[166:167], 0, v[236:237]
	global_load_dwordx4 v[204:207], v[236:237], off
	global_load_dwordx4 v[208:211], v[236:237], off offset:16
	global_load_dwordx4 v[212:215], v[236:237], off offset:512
	global_load_dwordx4 v[216:219], v[236:237], off offset:528
	v_add_u32_e32 v202, 0x90, v164
	v_ashrrev_i32_e32 v203, 31, v202
	v_lshlrev_b64 v[236:237], 12, v[202:203]
	v_lshl_add_u64 v[236:237], v[166:167], 0, v[236:237]
	global_load_dwordx4 v[220:223], v[236:237], off offset:16
	global_load_dwordx4 v[224:227], v[236:237], off
	global_load_dwordx4 v[228:231], v[236:237], off offset:528
	global_load_dwordx4 v[232:235], v[236:237], off offset:512
	v_lshlrev_b64 v[134:135], 11, v[116:117]
	v_lshl_add_u64 v[134:135], s[12:13], 0, v[134:135]
	v_lshl_add_u64 v[134:135], v[162:163], 1, v[134:135]
	v_pk_add_f32 v[94:95], v[94:95], v[118:119]
	v_pk_add_f32 v[96:97], v[96:97], v[120:121]
	v_pk_add_f32 v[92:93], v[92:93], v[124:125]
	v_pk_add_f32 v[90:91], v[90:91], v[122:123]
	v_pk_add_f32 v[120:121], v[86:87], v[126:127]
	v_mul_f32_e32 v126, v95, v95
	v_pk_add_f32 v[118:119], v[88:89], v[128:129]
	v_pk_add_f32 v[122:123], v[84:85], v[132:133]
	v_pk_add_f32 v[124:125], v[82:83], v[130:131]
	v_cvt_pk_bf16_f32 v82, v94, v95
	v_cvt_pk_bf16_f32 v83, v96, v97
	v_cvt_pk_bf16_f32 v84, v90, v91
	v_cvt_pk_bf16_f32 v85, v92, v93
	v_pk_fma_f32 v[94:95], v[94:95], v[94:95], v[126:127] op_sel_hi:[1,1,0]
	v_mul_f32_e32 v128, v97, v97
	v_cvt_pk_bf16_f32 v86, v120, v121
	v_cvt_pk_bf16_f32 v87, v118, v119
	v_cvt_pk_bf16_f32 v88, v124, v125
	v_cvt_pk_bf16_f32 v89, v122, v123
	global_store_dwordx4 v[134:135], v[82:85], off
	global_store_dwordx4 v[134:135], v[86:89], off offset:256
	v_mul_f32_e32 v130, v91, v91
	v_pk_fma_f32 v[82:83], v[96:97], v[96:97], v[94:95]
	v_mul_f32_e32 v132, v93, v93
	v_pk_add_f32 v[82:83], v[128:129], v[82:83] op_sel_hi:[0,1]
	v_pk_fma_f32 v[82:83], v[90:91], v[90:91], v[82:83]
	v_mul_f32_e32 v136, v121, v121
	v_pk_add_f32 v[82:83], v[130:131], v[82:83] op_sel_hi:[0,1]
	v_pk_fma_f32 v[82:83], v[92:93], v[92:93], v[82:83]
	v_mul_f32_e32 v138, v119, v119
	v_pk_add_f32 v[82:83], v[132:133], v[82:83] op_sel_hi:[0,1]
	v_pk_fma_f32 v[82:83], v[120:121], v[120:121], v[82:83]
	v_mul_f32_e32 v140, v125, v125
	v_pk_add_f32 v[82:83], v[136:137], v[82:83] op_sel_hi:[0,1]
	v_pk_fma_f32 v[82:83], v[118:119], v[118:119], v[82:83]
	v_mul_f32_e32 v142, v123, v123
	v_pk_add_f32 v[82:83], v[138:139], v[82:83] op_sel_hi:[0,1]
	v_pk_fma_f32 v[82:83], v[124:125], v[124:125], v[82:83]
	s_nop 0
	v_pk_add_f32 v[82:83], v[140:141], v[82:83] op_sel_hi:[0,1]
	v_pk_fma_f32 v[82:83], v[122:123], v[122:123], v[82:83]
	s_nop 0
	v_pk_add_f32 v[82:83], v[142:143], v[82:83] op_sel_hi:[0,1]
	v_mov_b32_e32 v83, v82
	s_nop 1
	v_permlane16_swap_b32_e32 v82, v83
	v_add_f32_e32 v82, v82, v83
	v_mov_b32_e32 v83, v82
	s_nop 1
	v_permlane32_swap_b32_e32 v82, v83
	s_and_saveexec_b64 s[30:31], s[0:1]
	s_cbranch_execz .LBB0_1443
	v_lshlrev_b64 v[84:85], 6, v[116:117]
	v_lshl_add_u64 v[84:85], s[14:15], 0, v[84:85]
	v_lshl_add_u64 v[84:85], s[28:29], 2, v[84:85]
	s_lshl_b32 s8, s45, 2
	v_lshl_add_u64 v[84:85], v[84:85], 0, s[8:9]
	v_add_f32_e32 v82, v82, v83
	global_store_dword v[84:85], v82, off
.LBB0_1443:
	s_or_b64 exec, exec, s[30:31]
	v_pk_add_f32 v[78:79], v[78:79], v[110:111]
	v_pk_add_f32 v[80:81], v[80:81], v[112:113]
	v_mul_f32_e32 v84, v79, v79
	v_pk_fma_f32 v[84:85], v[78:79], v[78:79], v[84:85] op_sel_hi:[1,1,0]
	v_mul_f32_e32 v86, v81, v81
	v_pk_fma_f32 v[84:85], v[80:81], v[80:81], v[84:85]
	v_lshlrev_b64 v[82:83], 11, v[114:115]
	v_pk_add_f32 v[84:85], v[86:87], v[84:85] op_sel_hi:[0,1]
	v_pk_add_f32 v[86:87], v[76:77], v[108:109]
	v_pk_add_f32 v[76:77], v[74:75], v[106:107]
	v_pk_add_f32 v[70:71], v[70:71], v[102:103]
	v_pk_fma_f32 v[74:75], v[76:77], v[76:77], v[84:85]
	v_mul_f32_e32 v84, v77, v77
	v_pk_add_f32 v[74:75], v[84:85], v[74:75] op_sel_hi:[0,1]
	v_pk_fma_f32 v[74:75], v[86:87], v[86:87], v[74:75]
	v_mul_f32_e32 v84, v87, v87
	v_pk_add_f32 v[84:85], v[84:85], v[74:75] op_sel_hi:[0,1]
	v_cvt_pk_bf16_f32 v74, v78, v79
	v_lshl_add_u64 v[78:79], s[12:13], 0, v[82:83]
	v_cvt_pk_bf16_f32 v75, v80, v81
	v_cvt_pk_bf16_f32 v76, v76, v77
	v_cvt_pk_bf16_f32 v77, v86, v87
	v_lshl_add_u64 v[78:79], v[162:163], 1, v[78:79]
	global_store_dwordx4 v[78:79], v[74:77], off
	v_pk_add_f32 v[72:73], v[72:73], v[104:105]
	s_nop 0
	v_pk_fma_f32 v[74:75], v[70:71], v[70:71], v[84:85]
	v_mul_f32_e32 v76, v71, v71
	v_pk_add_f32 v[74:75], v[76:77], v[74:75] op_sel_hi:[0,1]
	v_pk_fma_f32 v[74:75], v[72:73], v[72:73], v[74:75]
	v_mul_f32_e32 v76, v73, v73
	v_pk_add_f32 v[74:75], v[76:77], v[74:75] op_sel_hi:[0,1]
	v_pk_add_f32 v[76:77], v[68:69], v[100:101]
	v_pk_add_f32 v[68:69], v[66:67], v[98:99]
	s_nop 0
	v_pk_fma_f32 v[66:67], v[68:69], v[68:69], v[74:75]
	v_mul_f32_e32 v74, v69, v69
	v_pk_add_f32 v[66:67], v[74:75], v[66:67] op_sel_hi:[0,1]
	v_pk_fma_f32 v[66:67], v[76:77], v[76:77], v[66:67]
	v_mul_f32_e32 v74, v77, v77
	v_pk_add_f32 v[74:75], v[74:75], v[66:67] op_sel_hi:[0,1]
	v_cvt_pk_bf16_f32 v66, v70, v71
	v_cvt_pk_bf16_f32 v67, v72, v73
	v_cvt_pk_bf16_f32 v68, v68, v69
	v_cvt_pk_bf16_f32 v69, v76, v77
	global_store_dwordx4 v[78:79], v[66:69], off offset:256
	s_nop 1
	v_mov_b32_e32 v66, v74
	s_nop 1
	v_permlane16_swap_b32_e32 v74, v66
	v_add_f32_e32 v66, v74, v66
	v_mov_b32_e32 v67, v66
	s_nop 1
	v_permlane32_swap_b32_e32 v66, v67
	s_and_saveexec_b64 s[30:31], s[0:1]
	s_cbranch_execz .LBB0_1445
	v_lshlrev_b64 v[68:69], 6, v[114:115]
	v_lshl_add_u64 v[68:69], s[14:15], 0, v[68:69]
	v_lshl_add_u64 v[68:69], s[28:29], 2, v[68:69]
	s_lshl_b32 s8, s45, 2
	v_lshl_add_u64 v[68:69], v[68:69], 0, s[8:9]
	v_add_f32_e32 v66, v66, v67
	global_store_dword v[68:69], v66, off
.LBB0_1445:
	s_or_b64 exec, exec, s[30:31]
	v_add_u32_e32 v84, 0x80, v164
	v_ashrrev_i32_e32 v85, 31, v84
	v_lshlrev_b64 v[66:67], 12, v[84:85]
	v_lshl_add_u64 v[66:67], v[166:167], 0, v[66:67]
	v_add_u32_e32 v82, 0x90, v164
	v_ashrrev_i32_e32 v83, 31, v82
	v_lshlrev_b64 v[66:67], 12, v[82:83]
	v_lshl_add_u64 v[70:71], v[166:167], 0, v[66:67]
	s_nop 0
	s_waitcnt vmcnt(6)
	v_mov_b64_e32 v[86:87], v[204:205]
	v_mov_b64_e32 v[88:89], v[206:207]
	v_mov_b64_e32 v[90:91], v[208:209]
	v_mov_b64_e32 v[92:93], v[210:211]
	v_mov_b64_e32 v[94:95], v[212:213]
	v_mov_b64_e32 v[96:97], v[214:215]
	v_mov_b64_e32 v[98:99], v[216:217]
	v_mov_b64_e32 v[100:101], v[218:219]
	v_mov_b64_e32 v[74:75], v[220:221]
	v_mov_b64_e32 v[76:77], v[222:223]
	v_mov_b64_e32 v[78:79], v[224:225]
	v_mov_b64_e32 v[80:81], v[226:227]
	v_mov_b64_e32 v[66:67], v[228:229]
	v_mov_b64_e32 v[68:69], v[230:231]
	v_mov_b64_e32 v[70:71], v[232:233]
	v_mov_b64_e32 v[72:73], v[234:235]
	v_add_u32_e32 v202, 0xa0, v164
	v_ashrrev_i32_e32 v203, 31, v202
	v_lshlrev_b64 v[236:237], 12, v[202:203]
	v_lshl_add_u64 v[236:237], v[166:167], 0, v[236:237]
	global_load_dwordx4 v[204:207], v[236:237], off
	global_load_dwordx4 v[208:211], v[236:237], off offset:16
	global_load_dwordx4 v[212:215], v[236:237], off offset:512
	global_load_dwordx4 v[216:219], v[236:237], off offset:528
	v_add_u32_e32 v202, 0xb0, v164
	v_ashrrev_i32_e32 v203, 31, v202
	v_lshlrev_b64 v[236:237], 12, v[202:203]
	v_lshl_add_u64 v[236:237], v[166:167], 0, v[236:237]
	global_load_dwordx4 v[220:223], v[236:237], off offset:16
	global_load_dwordx4 v[224:227], v[236:237], off
	global_load_dwordx4 v[228:231], v[236:237], off offset:528
	global_load_dwordx4 v[232:235], v[236:237], off offset:512
	v_lshlrev_b64 v[102:103], 11, v[84:85]
	v_lshl_add_u64 v[102:103], s[12:13], 0, v[102:103]
	v_lshl_add_u64 v[102:103], v[162:163], 1, v[102:103]
	v_pk_add_f32 v[62:63], v[62:63], v[86:87]
	v_pk_add_f32 v[64:65], v[64:65], v[88:89]
	v_pk_add_f32 v[60:61], v[60:61], v[92:93]
	v_pk_add_f32 v[58:59], v[58:59], v[90:91]
	v_pk_add_f32 v[88:89], v[54:55], v[94:95]
	v_mul_f32_e32 v94, v63, v63
	v_pk_add_f32 v[86:87], v[56:57], v[96:97]
	v_pk_add_f32 v[90:91], v[52:53], v[100:101]
	v_pk_add_f32 v[92:93], v[50:51], v[98:99]
	v_cvt_pk_bf16_f32 v50, v62, v63
	v_cvt_pk_bf16_f32 v51, v64, v65
	v_cvt_pk_bf16_f32 v52, v58, v59
	v_cvt_pk_bf16_f32 v53, v60, v61
	v_pk_fma_f32 v[62:63], v[62:63], v[62:63], v[94:95] op_sel_hi:[1,1,0]
	v_mul_f32_e32 v96, v65, v65
	v_cvt_pk_bf16_f32 v54, v88, v89
	v_cvt_pk_bf16_f32 v55, v86, v87
	v_cvt_pk_bf16_f32 v56, v92, v93
	v_cvt_pk_bf16_f32 v57, v90, v91
	global_store_dwordx4 v[102:103], v[50:53], off
	global_store_dwordx4 v[102:103], v[54:57], off offset:256
	v_mul_f32_e32 v98, v59, v59
	v_pk_fma_f32 v[50:51], v[64:65], v[64:65], v[62:63]
	v_mul_f32_e32 v100, v61, v61
	v_pk_add_f32 v[50:51], v[96:97], v[50:51] op_sel_hi:[0,1]
	v_pk_fma_f32 v[50:51], v[58:59], v[58:59], v[50:51]
	v_mul_f32_e32 v104, v89, v89
	v_pk_add_f32 v[50:51], v[98:99], v[50:51] op_sel_hi:[0,1]
	v_pk_fma_f32 v[50:51], v[60:61], v[60:61], v[50:51]
	v_mul_f32_e32 v106, v87, v87
	v_pk_add_f32 v[50:51], v[100:101], v[50:51] op_sel_hi:[0,1]
	v_pk_fma_f32 v[50:51], v[88:89], v[88:89], v[50:51]
	v_mul_f32_e32 v108, v93, v93
	v_pk_add_f32 v[50:51], v[104:105], v[50:51] op_sel_hi:[0,1]
	v_pk_fma_f32 v[50:51], v[86:87], v[86:87], v[50:51]
	v_mul_f32_e32 v110, v91, v91
	v_pk_add_f32 v[50:51], v[106:107], v[50:51] op_sel_hi:[0,1]
	v_pk_fma_f32 v[50:51], v[92:93], v[92:93], v[50:51]
	s_nop 0
	v_pk_add_f32 v[50:51], v[108:109], v[50:51] op_sel_hi:[0,1]
	v_pk_fma_f32 v[50:51], v[90:91], v[90:91], v[50:51]
	s_nop 0
	v_pk_add_f32 v[50:51], v[110:111], v[50:51] op_sel_hi:[0,1]
	v_mov_b32_e32 v51, v50
	s_nop 1
	v_permlane16_swap_b32_e32 v50, v51
	v_add_f32_e32 v50, v50, v51
	v_mov_b32_e32 v51, v50
	s_nop 1
	v_permlane32_swap_b32_e32 v50, v51
	s_and_saveexec_b64 s[30:31], s[0:1]
	s_cbranch_execz .LBB0_1447
	v_lshlrev_b64 v[52:53], 6, v[84:85]
	v_lshl_add_u64 v[52:53], s[14:15], 0, v[52:53]
	v_lshl_add_u64 v[52:53], s[28:29], 2, v[52:53]
	s_lshl_b32 s8, s45, 2
	v_lshl_add_u64 v[52:53], v[52:53], 0, s[8:9]
	v_add_f32_e32 v50, v50, v51
	global_store_dword v[52:53], v50, off
.LBB0_1447:
	s_or_b64 exec, exec, s[30:31]
	v_pk_add_f32 v[46:47], v[46:47], v[78:79]
	v_pk_add_f32 v[48:49], v[48:49], v[80:81]
	v_mul_f32_e32 v52, v47, v47
	v_pk_fma_f32 v[52:53], v[46:47], v[46:47], v[52:53] op_sel_hi:[1,1,0]
	v_mul_f32_e32 v54, v49, v49
	v_pk_fma_f32 v[52:53], v[48:49], v[48:49], v[52:53]
	v_lshlrev_b64 v[50:51], 11, v[82:83]
	v_pk_add_f32 v[52:53], v[54:55], v[52:53] op_sel_hi:[0,1]
	v_pk_add_f32 v[54:55], v[44:45], v[76:77]
	v_pk_add_f32 v[44:45], v[42:43], v[74:75]
	v_pk_add_f32 v[38:39], v[38:39], v[70:71]
	v_pk_fma_f32 v[42:43], v[44:45], v[44:45], v[52:53]
	v_mul_f32_e32 v52, v45, v45
	v_pk_add_f32 v[42:43], v[52:53], v[42:43] op_sel_hi:[0,1]
	v_pk_fma_f32 v[42:43], v[54:55], v[54:55], v[42:43]
	v_mul_f32_e32 v52, v55, v55
	v_pk_add_f32 v[52:53], v[52:53], v[42:43] op_sel_hi:[0,1]
	v_cvt_pk_bf16_f32 v42, v46, v47
	v_lshl_add_u64 v[46:47], s[12:13], 0, v[50:51]
	v_cvt_pk_bf16_f32 v43, v48, v49
	v_cvt_pk_bf16_f32 v44, v44, v45
	v_cvt_pk_bf16_f32 v45, v54, v55
	v_lshl_add_u64 v[46:47], v[162:163], 1, v[46:47]
	global_store_dwordx4 v[46:47], v[42:45], off
	v_pk_add_f32 v[40:41], v[40:41], v[72:73]
	s_nop 0
	v_pk_fma_f32 v[42:43], v[38:39], v[38:39], v[52:53]
	v_mul_f32_e32 v44, v39, v39
	v_pk_add_f32 v[42:43], v[44:45], v[42:43] op_sel_hi:[0,1]
	v_pk_fma_f32 v[42:43], v[40:41], v[40:41], v[42:43]
	v_mul_f32_e32 v44, v41, v41
	v_pk_add_f32 v[42:43], v[44:45], v[42:43] op_sel_hi:[0,1]
	v_pk_add_f32 v[44:45], v[36:37], v[68:69]
	v_pk_add_f32 v[36:37], v[34:35], v[66:67]
	s_nop 0
	v_pk_fma_f32 v[34:35], v[36:37], v[36:37], v[42:43]
	v_mul_f32_e32 v42, v37, v37
	v_pk_add_f32 v[34:35], v[42:43], v[34:35] op_sel_hi:[0,1]
	v_pk_fma_f32 v[34:35], v[44:45], v[44:45], v[34:35]
	v_mul_f32_e32 v42, v45, v45
	v_pk_add_f32 v[42:43], v[42:43], v[34:35] op_sel_hi:[0,1]
	v_cvt_pk_bf16_f32 v34, v38, v39
	v_cvt_pk_bf16_f32 v35, v40, v41
	v_cvt_pk_bf16_f32 v36, v36, v37
	v_cvt_pk_bf16_f32 v37, v44, v45
	global_store_dwordx4 v[46:47], v[34:37], off offset:256
	s_nop 1
	v_mov_b32_e32 v34, v42
	s_nop 1
	v_permlane16_swap_b32_e32 v42, v34
	v_add_f32_e32 v34, v42, v34
	v_mov_b32_e32 v35, v34
	s_nop 1
	v_permlane32_swap_b32_e32 v34, v35
	s_and_saveexec_b64 s[30:31], s[0:1]
	s_cbranch_execz .LBB0_1449
	v_lshlrev_b64 v[36:37], 6, v[82:83]
	v_lshl_add_u64 v[36:37], s[14:15], 0, v[36:37]
	v_lshl_add_u64 v[36:37], s[28:29], 2, v[36:37]
	s_lshl_b32 s8, s45, 2
	v_lshl_add_u64 v[36:37], v[36:37], 0, s[8:9]
	v_add_f32_e32 v34, v34, v35
	global_store_dword v[36:37], v34, off
.LBB0_1449:
	s_or_b64 exec, exec, s[30:31]
	v_add_u32_e32 v52, 0xa0, v164
	v_ashrrev_i32_e32 v53, 31, v52
	v_lshlrev_b64 v[34:35], 12, v[52:53]
	v_lshl_add_u64 v[34:35], v[166:167], 0, v[34:35]
	v_add_u32_e32 v50, 0xb0, v164
	v_ashrrev_i32_e32 v51, 31, v50
	v_lshlrev_b64 v[34:35], 12, v[50:51]
	v_lshl_add_u64 v[38:39], v[166:167], 0, v[34:35]
	s_nop 0
	s_waitcnt vmcnt(6)
	v_mov_b64_e32 v[54:55], v[204:205]
	v_mov_b64_e32 v[56:57], v[206:207]
	v_mov_b64_e32 v[58:59], v[208:209]
	v_mov_b64_e32 v[60:61], v[210:211]
	v_mov_b64_e32 v[62:63], v[212:213]
	v_mov_b64_e32 v[64:65], v[214:215]
	v_mov_b64_e32 v[66:67], v[216:217]
	v_mov_b64_e32 v[68:69], v[218:219]
	v_mov_b64_e32 v[42:43], v[220:221]
	v_mov_b64_e32 v[44:45], v[222:223]
	v_mov_b64_e32 v[46:47], v[224:225]
	v_mov_b64_e32 v[48:49], v[226:227]
	v_mov_b64_e32 v[34:35], v[228:229]
	v_mov_b64_e32 v[36:37], v[230:231]
	v_mov_b64_e32 v[38:39], v[232:233]
	v_mov_b64_e32 v[40:41], v[234:235]
	v_lshlrev_b64 v[70:71], 11, v[52:53]
	v_lshl_add_u64 v[70:71], s[12:13], 0, v[70:71]
	v_lshl_add_u64 v[70:71], v[162:163], 1, v[70:71]
	v_pk_add_f32 v[30:31], v[30:31], v[54:55]
	v_pk_add_f32 v[32:33], v[32:33], v[56:57]
	v_pk_add_f32 v[28:29], v[28:29], v[60:61]
	v_pk_add_f32 v[26:27], v[26:27], v[58:59]
	v_pk_add_f32 v[56:57], v[22:23], v[62:63]
	v_mul_f32_e32 v62, v31, v31
	v_pk_add_f32 v[54:55], v[24:25], v[64:65]
	v_pk_add_f32 v[58:59], v[20:21], v[68:69]
	v_pk_add_f32 v[60:61], v[18:19], v[66:67]
	v_cvt_pk_bf16_f32 v18, v30, v31
	v_cvt_pk_bf16_f32 v19, v32, v33
	v_cvt_pk_bf16_f32 v20, v26, v27
	v_cvt_pk_bf16_f32 v21, v28, v29
	v_pk_fma_f32 v[30:31], v[30:31], v[30:31], v[62:63] op_sel_hi:[1,1,0]
	v_mul_f32_e32 v64, v33, v33
	v_cvt_pk_bf16_f32 v22, v56, v57
	v_cvt_pk_bf16_f32 v23, v54, v55
	v_cvt_pk_bf16_f32 v24, v60, v61
	v_cvt_pk_bf16_f32 v25, v58, v59
	global_store_dwordx4 v[70:71], v[18:21], off
	global_store_dwordx4 v[70:71], v[22:25], off offset:256
	v_mul_f32_e32 v66, v27, v27
	v_pk_fma_f32 v[18:19], v[32:33], v[32:33], v[30:31]
	v_mul_f32_e32 v68, v29, v29
	v_pk_add_f32 v[18:19], v[64:65], v[18:19] op_sel_hi:[0,1]
	v_pk_fma_f32 v[18:19], v[26:27], v[26:27], v[18:19]
	v_mul_f32_e32 v72, v57, v57
	v_pk_add_f32 v[18:19], v[66:67], v[18:19] op_sel_hi:[0,1]
	v_pk_fma_f32 v[18:19], v[28:29], v[28:29], v[18:19]
	v_mul_f32_e32 v74, v55, v55
	v_pk_add_f32 v[18:19], v[68:69], v[18:19] op_sel_hi:[0,1]
	v_pk_fma_f32 v[18:19], v[56:57], v[56:57], v[18:19]
	v_mul_f32_e32 v76, v61, v61
	v_pk_add_f32 v[18:19], v[72:73], v[18:19] op_sel_hi:[0,1]
	v_pk_fma_f32 v[18:19], v[54:55], v[54:55], v[18:19]
	v_mul_f32_e32 v78, v59, v59
	v_pk_add_f32 v[18:19], v[74:75], v[18:19] op_sel_hi:[0,1]
	v_pk_fma_f32 v[18:19], v[60:61], v[60:61], v[18:19]
	s_nop 0
	v_pk_add_f32 v[18:19], v[76:77], v[18:19] op_sel_hi:[0,1]
	v_pk_fma_f32 v[18:19], v[58:59], v[58:59], v[18:19]
	s_nop 0
	v_pk_add_f32 v[18:19], v[78:79], v[18:19] op_sel_hi:[0,1]
	v_mov_b32_e32 v19, v18
	s_nop 1
	v_permlane16_swap_b32_e32 v18, v19
	v_add_f32_e32 v18, v18, v19
	v_mov_b32_e32 v19, v18
	s_nop 1
	v_permlane32_swap_b32_e32 v18, v19
	s_and_saveexec_b64 s[30:31], s[0:1]
	s_cbranch_execz .LBB0_1451
	v_lshlrev_b64 v[20:21], 6, v[52:53]
	v_lshl_add_u64 v[20:21], s[14:15], 0, v[20:21]
	v_lshl_add_u64 v[20:21], s[28:29], 2, v[20:21]
	s_lshl_b32 s8, s45, 2
	v_lshl_add_u64 v[20:21], v[20:21], 0, s[8:9]
	v_add_f32_e32 v18, v18, v19
	global_store_dword v[20:21], v18, off
.LBB0_1451:
	s_or_b64 exec, exec, s[30:31]
	v_pk_add_f32 v[14:15], v[14:15], v[46:47]
	v_pk_add_f32 v[16:17], v[16:17], v[48:49]
	v_mul_f32_e32 v20, v15, v15
	v_pk_fma_f32 v[20:21], v[14:15], v[14:15], v[20:21] op_sel_hi:[1,1,0]
	v_mul_f32_e32 v22, v17, v17
	v_pk_fma_f32 v[20:21], v[16:17], v[16:17], v[20:21]
	v_lshlrev_b64 v[18:19], 11, v[50:51]
	v_pk_add_f32 v[20:21], v[22:23], v[20:21] op_sel_hi:[0,1]
	v_pk_add_f32 v[22:23], v[12:13], v[44:45]
	v_pk_add_f32 v[12:13], v[10:11], v[42:43]
	v_pk_add_f32 v[6:7], v[6:7], v[38:39]
	v_pk_fma_f32 v[10:11], v[12:13], v[12:13], v[20:21]
	v_mul_f32_e32 v20, v13, v13
	v_pk_add_f32 v[10:11], v[20:21], v[10:11] op_sel_hi:[0,1]
	v_pk_fma_f32 v[10:11], v[22:23], v[22:23], v[10:11]
	v_mul_f32_e32 v20, v23, v23
	v_pk_add_f32 v[20:21], v[20:21], v[10:11] op_sel_hi:[0,1]
	v_cvt_pk_bf16_f32 v10, v14, v15
	v_lshl_add_u64 v[14:15], s[12:13], 0, v[18:19]
	v_cvt_pk_bf16_f32 v11, v16, v17
	v_cvt_pk_bf16_f32 v12, v12, v13
	v_cvt_pk_bf16_f32 v13, v22, v23
	v_lshl_add_u64 v[14:15], v[162:163], 1, v[14:15]
	global_store_dwordx4 v[14:15], v[10:13], off
	v_pk_add_f32 v[8:9], v[8:9], v[40:41]
	s_nop 0
	v_pk_fma_f32 v[10:11], v[6:7], v[6:7], v[20:21]
	v_mul_f32_e32 v12, v7, v7
	v_pk_add_f32 v[10:11], v[12:13], v[10:11] op_sel_hi:[0,1]
	v_pk_fma_f32 v[10:11], v[8:9], v[8:9], v[10:11]
	v_mul_f32_e32 v12, v9, v9
	v_pk_add_f32 v[10:11], v[12:13], v[10:11] op_sel_hi:[0,1]
	v_pk_add_f32 v[12:13], v[4:5], v[36:37]
	v_pk_add_f32 v[4:5], v[2:3], v[34:35]
	s_nop 0
	v_pk_fma_f32 v[2:3], v[4:5], v[4:5], v[10:11]
	v_mul_f32_e32 v10, v5, v5
	v_pk_add_f32 v[2:3], v[10:11], v[2:3] op_sel_hi:[0,1]
	v_pk_fma_f32 v[2:3], v[12:13], v[12:13], v[2:3]
	v_mul_f32_e32 v10, v13, v13
	v_pk_add_f32 v[10:11], v[10:11], v[2:3] op_sel_hi:[0,1]
	v_cvt_pk_bf16_f32 v2, v6, v7
	v_cvt_pk_bf16_f32 v3, v8, v9
	v_cvt_pk_bf16_f32 v4, v4, v5
	v_cvt_pk_bf16_f32 v5, v12, v13
	global_store_dwordx4 v[14:15], v[2:5], off offset:256
	s_nop 1
	v_mov_b32_e32 v2, v10
	s_nop 1
	v_permlane16_swap_b32_e32 v10, v2
	v_add_f32_e32 v2, v10, v2
	v_mov_b32_e32 v3, v2
	s_nop 1
	v_permlane32_swap_b32_e32 v2, v3
	s_and_saveexec_b64 s[30:31], s[0:1]
	s_cbranch_execz .LBB0_1453
	v_lshlrev_b64 v[4:5], 6, v[50:51]
	v_lshl_add_u64 v[4:5], s[14:15], 0, v[4:5]
	v_lshl_add_u64 v[4:5], s[28:29], 2, v[4:5]
	s_lshl_b32 s8, s45, 2
	v_lshl_add_u64 v[4:5], v[4:5], 0, s[8:9]
	v_add_f32_e32 v2, v2, v3
	global_store_dword v[4:5], v2, off

.LBB0_1457:
	s_cmp_gt_i32 s83, 12
	s_cselect_b64 s[0:1], -1, 0
	s_and_b64 s[4:5], s[6:7], s[0:1]
	s_andn2_b64 vcc, exec, s[4:5]
	s_cbranch_vccnz .LBB0_1511
	s_waitcnt vmcnt(0)
	s_waitcnt vmcnt(0) lgkmcnt(0)
	s_barrier
	s_and_saveexec_b64 s[4:5], s[38:39]
	s_cbranch_execz .LBB0_1510
	s_add_u32 s98, s98, 1
	v_readlane_b32 s6, v238, 18
	v_readlane_b32 s7, v238, 19
	v_mov_b32_e32 v1, 0x25f20
	ds_read_b64 v[2:3], v1
	s_lshl_b32 s2, s87, 8
	s_addk_i32 s2, 0x1400
	v_mov_b32_e32 v1, s2
	v_mov_b32_e32 v5, 1
	v_readlane_b32 s12, v238, 63
	s_waitcnt lgkmcnt(0)
	v_readfirstlane_b32 s9, v2
	v_readfirstlane_b32 s10, v3
	s_mul_i32 s9, s9, s98
	s_cmp_lg_u32 s12, 0
	s_cselect_b32 s12, s98, 8
	s_mul_i32 s10, s10, s12
	global_atomic_add v1, v1, v5, s[6:7] sc0
	s_waitcnt vmcnt(0)
	v_readfirstlane_b32 s12, v1
	s_add_u32 s12, s12, 1
	v_mov_b32_e32 v1, 0x3400
	s_cmp_eq_u32 s12, s9
	s_cbranch_scc0 .Lfs7_spin
	buffer_wbl2 sc1
	s_waitcnt vmcnt(0)
	global_atomic_add v1, v5, s[6:7]

.LBB0_1528:
	s_cmp_gt_i32 s83, 13
	s_cselect_b64 s[0:1], -1, 0
	s_and_b64 s[4:5], s[4:5], s[0:1]
	s_andn2_b64 vcc, exec, s[4:5]
	s_cbranch_vccnz .LBB0_1582
	s_waitcnt vmcnt(0)
	s_waitcnt vmcnt(0) lgkmcnt(0)
	s_barrier
	s_and_saveexec_b64 s[4:5], s[38:39]
	s_cbranch_execz .LBB0_1581
	s_add_u32 s98, s98, 1
	v_readlane_b32 s6, v238, 18
	v_readlane_b32 s7, v238, 19
	v_mov_b32_e32 v1, 0x25f20
	ds_read_b64 v[2:3], v1
	s_lshl_b32 s2, s87, 8
	s_addk_i32 s2, 0x1400
	v_mov_b32_e32 v1, s2
	v_mov_b32_e32 v5, 1
	v_readlane_b32 s12, v238, 63
	s_waitcnt lgkmcnt(0)
	v_readfirstlane_b32 s9, v2
	v_readfirstlane_b32 s10, v3
	s_mul_i32 s9, s9, s98
	s_cmp_lg_u32 s12, 0
	s_cbranch_scc1 .Lfs8_glob
	global_atomic_add v1, v5, s[6:7]
	s_mov_b32 s11, 0

.LBB0_1607:
	v_lshl_add_u32 v148, s40, 8, v152
	v_lshl_or_b32 v144, s41, 8, v154
	v_ashrrev_i32_e32 v145, 31, v144
	v_ashrrev_i32_e32 v149, 31, v148
	v_lshl_add_u64 v[146:147], v[144:145], 1, s[8:9]
	v_lshlrev_b64 v[150:151], 11, v[148:149]
	v_or_b32_e32 v178, 16, v148
	v_lshl_add_u64 v[150:151], v[146:147], 0, v[150:151]
	v_ashrrev_i32_e32 v179, 31, v178
	global_load_dwordx4 v[158:161], v[150:151], off
	global_load_dwordx4 v[162:165], v[150:151], off offset:256
	v_lshlrev_b64 v[150:151], 11, v[178:179]
	v_or_b32_e32 v190, 32, v148
	v_lshl_add_u64 v[150:151], v[146:147], 0, v[150:151]
	v_ashrrev_i32_e32 v191, 31, v190
	global_load_dwordx4 v[166:169], v[150:151], off
	global_load_dwordx4 v[170:173], v[150:151], off offset:256
	v_lshlrev_b64 v[150:151], 11, v[190:191]
	v_lshl_add_u64 v[180:181], v[146:147], 0, v[150:151]
	global_load_dwordx4 v[174:177], v[180:181], off
	v_lshlrev_b64 v[186:187], 12, v[178:179]
	global_load_dwordx4 v[178:181], v[180:181], off offset:256
	v_or_b32_e32 v150, 48, v148
	v_ashrrev_i32_e32 v151, 31, v150
	v_lshlrev_b64 v[182:183], 12, v[148:149]
	v_lshlrev_b64 v[184:185], 11, v[150:151]
	v_lshlrev_b64 v[144:145], 2, v[144:145]
	v_lshl_add_u64 v[182:183], s[62:63], 0, v[182:183]
	v_lshl_add_u64 v[188:189], v[146:147], 0, v[184:185]
	v_lshl_add_u64 v[192:193], v[182:183], 0, v[144:145]
	v_lshl_add_u64 v[194:195], s[62:63], 0, v[186:187]
	global_load_dwordx4 v[182:185], v[188:189], off
	s_nop 0
	global_load_dwordx4 v[186:189], v[188:189], off offset:256
	v_add_u32_e32 v240, 0x80, v148
	v_ashrrev_i32_e32 v241, 31, v240
	v_lshlrev_b64 v[236:237], 11, v[240:241]
	v_lshl_add_u64 v[236:237], v[146:147], 0, v[236:237]
	global_load_dwordx4 v[204:207], v[236:237], off
	global_load_dwordx4 v[208:211], v[236:237], off offset:256
	v_add_u32_e32 v240, 0x90, v148
	v_ashrrev_i32_e32 v241, 31, v240
	v_lshlrev_b64 v[236:237], 11, v[240:241]
	v_lshl_add_u64 v[236:237], v[146:147], 0, v[236:237]
	global_load_dwordx4 v[212:215], v[236:237], off
	global_load_dwordx4 v[216:219], v[236:237], off offset:256
	v_add_u32_e32 v240, 0xa0, v148
	v_ashrrev_i32_e32 v241, 31, v240
	v_lshlrev_b64 v[236:237], 11, v[240:241]
	v_lshl_add_u64 v[236:237], v[146:147], 0, v[236:237]
	global_load_dwordx4 v[220:223], v[236:237], off
	global_load_dwordx4 v[224:227], v[236:237], off offset:256
	v_add_u32_e32 v240, 0xb0, v148
	v_ashrrev_i32_e32 v241, 31, v240
	v_lshlrev_b64 v[236:237], 11, v[240:241]
	v_lshl_add_u64 v[236:237], v[146:147], 0, v[236:237]
	global_load_dwordx4 v[228:231], v[236:237], off
	global_load_dwordx4 v[232:235], v[236:237], off offset:256
	v_lshl_add_u64 v[194:195], v[194:195], 0, v[144:145]
	s_and_b64 vcc, exec, s[0:1]
	s_mov_b64 s[0:1], -1
	s_waitcnt vmcnt(8)
	v_lshlrev_b32_e32 v196, 16, v158
	v_and_b32_e32 v197, 0xffff0000, v158
	v_lshlrev_b32_e32 v158, 16, v159
	v_and_b32_e32 v159, 0xffff0000, v159
	v_lshlrev_b32_e32 v198, 16, v160
	v_and_b32_e32 v199, 0xffff0000, v160
	v_lshlrev_b32_e32 v160, 16, v161
	v_and_b32_e32 v161, 0xffff0000, v161
	v_lshlrev_b32_e32 v200, 16, v162
	v_and_b32_e32 v201, 0xffff0000, v162
	v_lshlrev_b32_e32 v162, 16, v163
	v_and_b32_e32 v163, 0xffff0000, v163
	v_lshlrev_b32_e32 v202, 16, v164
	v_and_b32_e32 v203, 0xffff0000, v164
	v_lshlrev_b32_e32 v164, 16, v165
	v_and_b32_e32 v165, 0xffff0000, v165
	v_pk_add_f32 v[126:127], v[126:127], v[158:159]
	v_pk_add_f32 v[122:123], v[122:123], v[160:161]
	v_pk_add_f32 v[118:119], v[118:119], v[162:163]
	v_pk_add_f32 v[114:115], v[114:115], v[164:165]
	v_lshlrev_b32_e32 v158, 16, v166
	v_and_b32_e32 v159, 0xffff0000, v166
	v_lshlrev_b32_e32 v160, 16, v167
	v_and_b32_e32 v161, 0xffff0000, v167
	v_lshlrev_b32_e32 v162, 16, v168
	v_and_b32_e32 v163, 0xffff0000, v168
	v_lshlrev_b32_e32 v164, 16, v169
	v_and_b32_e32 v165, 0xffff0000, v169
	v_lshlrev_b32_e32 v166, 16, v170
	v_and_b32_e32 v167, 0xffff0000, v170
	v_lshlrev_b32_e32 v168, 16, v171
	v_and_b32_e32 v169, 0xffff0000, v171
	v_lshlrev_b32_e32 v170, 16, v172
	v_and_b32_e32 v171, 0xffff0000, v172
	v_pk_add_f32 v[124:125], v[124:125], v[196:197]
	v_lshlrev_b32_e32 v172, 16, v173
	v_and_b32_e32 v173, 0xffff0000, v173
	v_pk_add_f32 v[108:109], v[108:109], v[158:159]
	v_pk_add_f32 v[110:111], v[110:111], v[160:161]
	v_pk_add_f32 v[100:101], v[100:101], v[166:167]
	v_pk_add_f32 v[102:103], v[102:103], v[168:169]
	v_pk_add_f32 v[92:93], v[92:93], v[170:171]
	v_pk_add_f32 v[120:121], v[120:121], v[198:199]
	v_pk_add_f32 v[116:117], v[116:117], v[200:201]
	v_pk_add_f32 v[112:113], v[112:113], v[202:203]
	global_store_dwordx4 v[192:193], v[124:127], off
	global_store_dwordx4 v[192:193], v[120:123], off offset:16
	global_store_dwordx4 v[192:193], v[116:119], off offset:512
	global_store_dwordx4 v[192:193], v[112:115], off offset:528
	v_pk_add_f32 v[104:105], v[104:105], v[162:163]
	v_pk_add_f32 v[106:107], v[106:107], v[164:165]
	global_store_dwordx4 v[194:195], v[108:111], off
	global_store_dwordx4 v[194:195], v[104:107], off offset:16
	v_pk_add_f32 v[94:95], v[94:95], v[172:173]
	global_store_dwordx4 v[194:195], v[100:103], off offset:512
	global_store_dwordx4 v[194:195], v[92:95], off offset:528
	s_nop 0
	v_lshlrev_b64 v[100:101], 12, v[190:191]
	v_lshlrev_b32_e32 v92, 16, v174
	v_and_b32_e32 v93, 0xffff0000, v174
	v_pk_add_f32 v[92:93], v[96:97], v[92:93]
	v_lshlrev_b32_e32 v96, 16, v176
	v_and_b32_e32 v97, 0xffff0000, v176
	v_pk_add_f32 v[88:89], v[88:89], v[96:97]
	v_lshlrev_b32_e32 v96, 16, v177
	v_and_b32_e32 v97, 0xffff0000, v177
	v_lshlrev_b32_e32 v94, 16, v175
	v_and_b32_e32 v95, 0xffff0000, v175
	v_pk_add_f32 v[90:91], v[90:91], v[96:97]
	v_lshl_add_u64 v[96:97], s[62:63], 0, v[100:101]
	v_pk_add_f32 v[94:95], v[98:99], v[94:95]
	v_lshl_add_u64 v[96:97], v[96:97], 0, v[144:145]
	global_store_dwordx4 v[96:97], v[92:95], off
	global_store_dwordx4 v[96:97], v[88:91], off offset:16
	v_add_u32_e32 v98, 0x90, v148
	v_ashrrev_i32_e32 v99, 31, v98
	v_lshlrev_b32_e32 v88, 16, v178
	v_and_b32_e32 v89, 0xffff0000, v178
	v_pk_add_f32 v[84:85], v[84:85], v[88:89]
	v_lshlrev_b32_e32 v88, 16, v179
	v_and_b32_e32 v89, 0xffff0000, v179
	v_pk_add_f32 v[86:87], v[86:87], v[88:89]
	v_lshlrev_b32_e32 v88, 16, v180
	v_and_b32_e32 v89, 0xffff0000, v180
	v_pk_add_f32 v[76:77], v[76:77], v[88:89]
	v_lshlrev_b32_e32 v88, 16, v181
	v_and_b32_e32 v89, 0xffff0000, v181
	v_pk_add_f32 v[78:79], v[78:79], v[88:89]
	global_store_dwordx4 v[96:97], v[84:87], off offset:512
	global_store_dwordx4 v[96:97], v[76:79], off offset:528
	v_add_u32_e32 v96, 0x80, v148
	v_lshlrev_b64 v[84:85], 12, v[150:151]
	v_lshlrev_b32_e32 v76, 16, v182
	v_and_b32_e32 v77, 0xffff0000, v182
	v_pk_add_f32 v[76:77], v[80:81], v[76:77]
	v_lshlrev_b32_e32 v80, 16, v184
	v_and_b32_e32 v81, 0xffff0000, v184
	v_pk_add_f32 v[72:73], v[72:73], v[80:81]
	v_lshlrev_b32_e32 v80, 16, v185
	v_and_b32_e32 v81, 0xffff0000, v185
	v_lshlrev_b32_e32 v78, 16, v183
	v_and_b32_e32 v79, 0xffff0000, v183
	v_pk_add_f32 v[74:75], v[74:75], v[80:81]
	v_lshl_add_u64 v[80:81], s[62:63], 0, v[84:85]
	v_pk_add_f32 v[78:79], v[82:83], v[78:79]
	v_lshl_add_u64 v[80:81], v[80:81], 0, v[144:145]
	global_store_dwordx4 v[80:81], v[76:79], off
	global_store_dwordx4 v[80:81], v[72:75], off offset:16
	v_ashrrev_i32_e32 v97, 31, v96
	v_add_u32_e32 v100, 0xa0, v148
	v_lshlrev_b32_e32 v72, 16, v186
	v_and_b32_e32 v73, 0xffff0000, v186
	v_pk_add_f32 v[68:69], v[68:69], v[72:73]
	v_lshlrev_b32_e32 v72, 16, v187
	v_and_b32_e32 v73, 0xffff0000, v187
	v_pk_add_f32 v[70:71], v[70:71], v[72:73]
	v_lshlrev_b32_e32 v72, 16, v188
	v_and_b32_e32 v73, 0xffff0000, v188
	v_pk_add_f32 v[64:65], v[64:65], v[72:73]
	v_lshlrev_b32_e32 v72, 16, v189
	v_and_b32_e32 v73, 0xffff0000, v189
	v_pk_add_f32 v[66:67], v[66:67], v[72:73]
	global_store_dwordx4 v[80:81], v[68:71], off offset:512
	global_store_dwordx4 v[80:81], v[64:67], off offset:528
	v_ashrrev_i32_e32 v101, 31, v100
	v_add_u32_e32 v102, 0xb0, v148
	v_lshlrev_b64 v[64:65], 11, v[96:97]
	v_lshl_add_u64 v[64:65], v[146:147], 0, v[64:65]
	v_lshlrev_b64 v[64:65], 11, v[98:99]
	v_lshl_add_u64 v[64:65], v[146:147], 0, v[64:65]
	v_lshlrev_b64 v[64:65], 11, v[100:101]
	v_lshl_add_u64 v[64:65], v[146:147], 0, v[64:65]
	v_ashrrev_i32_e32 v103, 31, v102
	v_lshlrev_b64 v[64:65], 11, v[102:103]
	v_lshl_add_u64 v[64:65], v[146:147], 0, v[64:65]
	s_nop 0
	s_waitcnt vmcnt(16)
	v_mov_b64_e32 v[68:69], v[204:205]
	v_mov_b64_e32 v[70:71], v[206:207]
	v_mov_b64_e32 v[72:73], v[208:209]
	v_mov_b64_e32 v[74:75], v[210:211]
	v_mov_b64_e32 v[76:77], v[212:213]
	v_mov_b64_e32 v[78:79], v[214:215]
	v_mov_b64_e32 v[80:81], v[216:217]
	v_mov_b64_e32 v[82:83], v[218:219]
	v_mov_b64_e32 v[84:85], v[220:221]
	v_mov_b64_e32 v[86:87], v[222:223]
	v_mov_b64_e32 v[88:89], v[224:225]
	v_mov_b64_e32 v[90:91], v[226:227]
	v_mov_b64_e32 v[92:93], v[228:229]
	v_mov_b64_e32 v[94:95], v[230:231]
	v_mov_b64_e32 v[64:65], v[232:233]
	v_mov_b64_e32 v[66:67], v[234:235]
	v_lshlrev_b64 v[96:97], 12, v[96:97]
	v_lshlrev_b32_e32 v104, 16, v68
	v_and_b32_e32 v105, 0xffff0000, v68
	v_lshlrev_b32_e32 v68, 16, v69
	v_and_b32_e32 v69, 0xffff0000, v69
	v_pk_add_f32 v[62:63], v[62:63], v[68:69]
	v_lshlrev_b32_e32 v68, 16, v70
	v_and_b32_e32 v69, 0xffff0000, v70
	v_pk_add_f32 v[56:57], v[56:57], v[68:69]
	v_lshlrev_b32_e32 v68, 16, v71
	v_and_b32_e32 v69, 0xffff0000, v71
	v_pk_add_f32 v[58:59], v[58:59], v[68:69]
	v_lshl_add_u64 v[68:69], s[62:63], 0, v[96:97]
	v_pk_add_f32 v[60:61], v[60:61], v[104:105]
	v_lshl_add_u64 v[68:69], v[68:69], 0, v[144:145]
	global_store_dwordx4 v[68:69], v[60:63], off
	global_store_dwordx4 v[68:69], v[56:59], off offset:16
	s_nop 0
	v_lshlrev_b32_e32 v56, 16, v72
	v_and_b32_e32 v57, 0xffff0000, v72
	v_pk_add_f32 v[52:53], v[52:53], v[56:57]
	v_lshlrev_b32_e32 v56, 16, v73
	v_and_b32_e32 v57, 0xffff0000, v73
	v_pk_add_f32 v[54:55], v[54:55], v[56:57]
	v_lshlrev_b32_e32 v56, 16, v74
	v_and_b32_e32 v57, 0xffff0000, v74
	v_pk_add_f32 v[44:45], v[44:45], v[56:57]
	v_lshlrev_b32_e32 v56, 16, v75
	v_and_b32_e32 v57, 0xffff0000, v75
	v_pk_add_f32 v[46:47], v[46:47], v[56:57]
	global_store_dwordx4 v[68:69], v[52:55], off offset:512
	global_store_dwordx4 v[68:69], v[44:47], off offset:528
	s_nop 0
	v_lshlrev_b64 v[52:53], 12, v[98:99]
	v_lshlrev_b32_e32 v44, 16, v76
	v_and_b32_e32 v45, 0xffff0000, v76
	v_pk_add_f32 v[44:45], v[48:49], v[44:45]
	v_lshlrev_b32_e32 v48, 16, v78
	v_and_b32_e32 v49, 0xffff0000, v78
	v_pk_add_f32 v[40:41], v[40:41], v[48:49]
	v_lshlrev_b32_e32 v48, 16, v79
	v_and_b32_e32 v49, 0xffff0000, v79
	v_lshlrev_b32_e32 v46, 16, v77
	v_and_b32_e32 v47, 0xffff0000, v77
	v_pk_add_f32 v[42:43], v[42:43], v[48:49]
	v_lshl_add_u64 v[48:49], s[62:63], 0, v[52:53]
	v_pk_add_f32 v[46:47], v[50:51], v[46:47]
	v_lshl_add_u64 v[48:49], v[48:49], 0, v[144:145]
	global_store_dwordx4 v[48:49], v[44:47], off
	global_store_dwordx4 v[48:49], v[40:43], off offset:16
	s_nop 0
	v_lshlrev_b32_e32 v40, 16, v80
	v_and_b32_e32 v41, 0xffff0000, v80
	v_pk_add_f32 v[36:37], v[36:37], v[40:41]
	v_lshlrev_b32_e32 v40, 16, v81
	v_and_b32_e32 v41, 0xffff0000, v81
	v_pk_add_f32 v[38:39], v[38:39], v[40:41]
	v_lshlrev_b32_e32 v40, 16, v82
	v_and_b32_e32 v41, 0xffff0000, v82
	v_pk_add_f32 v[28:29], v[28:29], v[40:41]
	v_lshlrev_b32_e32 v40, 16, v83
	v_and_b32_e32 v41, 0xffff0000, v83
	v_pk_add_f32 v[30:31], v[30:31], v[40:41]
	global_store_dwordx4 v[48:49], v[36:39], off offset:512
	global_store_dwordx4 v[48:49], v[28:31], off offset:528
	s_nop 0
	v_lshlrev_b64 v[36:37], 12, v[100:101]
	v_lshlrev_b32_e32 v28, 16, v84
	v_and_b32_e32 v29, 0xffff0000, v84
	v_pk_add_f32 v[28:29], v[32:33], v[28:29]
	v_lshlrev_b32_e32 v32, 16, v86
	v_and_b32_e32 v33, 0xffff0000, v86
	v_pk_add_f32 v[24:25], v[24:25], v[32:33]
	v_lshlrev_b32_e32 v32, 16, v87
	v_and_b32_e32 v33, 0xffff0000, v87
	v_lshlrev_b32_e32 v30, 16, v85
	v_and_b32_e32 v31, 0xffff0000, v85
	v_pk_add_f32 v[26:27], v[26:27], v[32:33]
	v_lshl_add_u64 v[32:33], s[62:63], 0, v[36:37]
	v_pk_add_f32 v[30:31], v[34:35], v[30:31]
	v_lshl_add_u64 v[32:33], v[32:33], 0, v[144:145]
	global_store_dwordx4 v[32:33], v[28:31], off
	global_store_dwordx4 v[32:33], v[24:27], off offset:16
	s_nop 0
	v_lshlrev_b32_e32 v24, 16, v88
	v_and_b32_e32 v25, 0xffff0000, v88
	v_pk_add_f32 v[20:21], v[20:21], v[24:25]
	v_lshlrev_b32_e32 v24, 16, v89
	v_and_b32_e32 v25, 0xffff0000, v89
	v_pk_add_f32 v[22:23], v[22:23], v[24:25]
	v_lshlrev_b32_e32 v24, 16, v90
	v_and_b32_e32 v25, 0xffff0000, v90
	v_pk_add_f32 v[12:13], v[12:13], v[24:25]
	v_lshlrev_b32_e32 v24, 16, v91
	v_and_b32_e32 v25, 0xffff0000, v91
	v_pk_add_f32 v[14:15], v[14:15], v[24:25]
	global_store_dwordx4 v[32:33], v[20:23], off offset:512
	global_store_dwordx4 v[32:33], v[12:15], off offset:528
	s_nop 0
	v_lshlrev_b64 v[20:21], 12, v[102:103]
	v_lshlrev_b32_e32 v12, 16, v92
	v_and_b32_e32 v13, 0xffff0000, v92
	v_pk_add_f32 v[12:13], v[16:17], v[12:13]
	v_lshlrev_b32_e32 v16, 16, v94
	v_and_b32_e32 v17, 0xffff0000, v94
	v_pk_add_f32 v[8:9], v[8:9], v[16:17]
	v_lshlrev_b32_e32 v16, 16, v95
	v_and_b32_e32 v17, 0xffff0000, v95
	v_lshlrev_b32_e32 v14, 16, v93
	v_and_b32_e32 v15, 0xffff0000, v93
	v_pk_add_f32 v[10:11], v[10:11], v[16:17]
	v_lshl_add_u64 v[16:17], s[62:63], 0, v[20:21]
	v_pk_add_f32 v[14:15], v[18:19], v[14:15]
	v_lshl_add_u64 v[16:17], v[16:17], 0, v[144:145]
	global_store_dwordx4 v[16:17], v[12:15], off
	global_store_dwordx4 v[16:17], v[8:11], off offset:16
	s_nop 0
	v_lshlrev_b32_e32 v8, 16, v64
	v_and_b32_e32 v9, 0xffff0000, v64
	v_pk_add_f32 v[4:5], v[4:5], v[8:9]
	v_lshlrev_b32_e32 v8, 16, v65
	v_and_b32_e32 v9, 0xffff0000, v65
	v_pk_add_f32 v[6:7], v[6:7], v[8:9]
	v_lshlrev_b32_e32 v8, 16, v66
	v_and_b32_e32 v9, 0xffff0000, v66
	v_pk_add_f32 v[0:1], v[0:1], v[8:9]
	v_lshlrev_b32_e32 v8, 16, v67
	v_and_b32_e32 v9, 0xffff0000, v67
	v_pk_add_f32 v[2:3], v[2:3], v[8:9]
	global_store_dwordx4 v[16:17], v[4:7], off offset:512
	global_store_dwordx4 v[16:17], v[0:3], off offset:528
	s_cbranch_vccnz .LBB0_1592
	s_andn2_b64 vcc, exec, s[6:7]
	s_cbranch_vccnz .LBB0_1591
	s_barrier
	s_branch .LBB0_1591
